# up K-loop: first K-iteration peeled, its first MFMA per accumulator takes C=0 (no per-unit accumulator zeroing moves)
# speedup vs baseline: 1.1121x; 1.0009x over previous
.LBB0_46:
	s_mov_b32 s7, 16
	s_cmp_lt_i32 s7, 1
	s_cbranch_scc1 .LBB0_62
	s_add_i32 s33, s7, -2
	s_add_u32 s68, s8, 0x100
	s_addc_u32 s69, s9, 0
	s_add_u32 s4, s4, 0x40080
	s_mov_b64 s[84:85], s[54:55]
	s_addc_u32 s5, s5, 0
	s_mov_b32 s8, 0
	s_add_i32 s52, s8, 2
	s_add_u32 s9, s4, 0xfffc0080
	s_addc_u32 s53, s5, -1
	s_add_i32 s54, 0, 0x10000
	s_cmp_eq_u32 s33, s8
	s_cselect_b32 vcc_hi, s15, s53
	s_cselect_b32 vcc_lo, s14, s9
	s_cselect_b32 s9, s35, s69
	s_cselect_b32 s8, s34, s68
	s_add_i32 s53, 0, 0x14000
	v_add_u32_e32 v140, s54, v188
	v_add_u32_e32 v156, s53, v188
	ds_read_b128 v[128:131], v140
	ds_read_b128 v[132:135], v140 offset:1024
	ds_read_b128 v[136:139], v140 offset:2048
	ds_read_b128 v[140:143], v140 offset:3072
	ds_read_b128 v[144:147], v156
	ds_read_b128 v[148:151], v156 offset:1024
	ds_read_b128 v[152:155], v156 offset:2048
	ds_read_b128 v[156:159], v156 offset:3072
	s_add_i32 m0, s10, 0xc000
	ds_read_b128 v[172:175], v189
	ds_read_b128 v[176:179], v189 offset:1024
	ds_read_b128 v[180:183], v189 offset:2048
	ds_read_b128 v[184:187], v189 offset:3072
	ds_read_b128 v[212:215], v189 offset:4096
	ds_read_b128 v[216:219], v189 offset:5120
	ds_read_b128 v[220:223], v189 offset:6144
	ds_read_b128 v[224:227], v189 offset:7168
	global_load_lds_dwordx4 v170, s[4:5]
	s_add_i32 m0, s10, 0xe000
	s_nop 0
	global_load_lds_dwordx4 v168, s[4:5]
	s_waitcnt vmcnt(8)
	s_waitcnt lgkmcnt(0)
	s_barrier
	s_setprio 1
	s_waitcnt lgkmcnt(0)
	v_mfma_f32_16x16x32_bf16 v[124:127], v[128:131], v[172:175], 0
	v_mfma_f32_16x16x32_bf16 v[60:63], v[136:139], v[172:175], 0
	v_mfma_f32_16x16x32_bf16 v[116:119], v[128:131], v[180:183], 0
	v_mfma_f32_16x16x32_bf16 v[52:55], v[136:139], v[180:183], 0
	v_mfma_f32_16x16x32_bf16 v[108:111], v[128:131], v[212:215], 0
	v_mfma_f32_16x16x32_bf16 v[44:47], v[136:139], v[212:215], 0
	v_mfma_f32_16x16x32_bf16 v[100:103], v[128:131], v[220:223], 0
	v_mfma_f32_16x16x32_bf16 v[36:39], v[136:139], v[220:223], 0
	v_mfma_f32_16x16x32_bf16 v[124:127], v[132:135], v[176:179], v[124:127]
	v_mfma_f32_16x16x32_bf16 v[60:63], v[140:143], v[176:179], v[60:63]
	v_mfma_f32_16x16x32_bf16 v[116:119], v[132:135], v[184:187], v[116:119]
	v_mfma_f32_16x16x32_bf16 v[52:55], v[140:143], v[184:187], v[52:55]
	v_mfma_f32_16x16x32_bf16 v[108:111], v[132:135], v[216:219], v[108:111]
	v_mfma_f32_16x16x32_bf16 v[44:47], v[140:143], v[216:219], v[44:47]
	v_mfma_f32_16x16x32_bf16 v[100:103], v[132:135], v[224:227], v[100:103]
	v_mfma_f32_16x16x32_bf16 v[36:39], v[140:143], v[224:227], v[36:39]
	s_setprio 0
	s_setprio 1
	v_mfma_f32_16x16x32_bf16 v[120:123], v[144:147], v[172:175], 0
	v_mfma_f32_16x16x32_bf16 v[56:59], v[152:155], v[172:175], 0
	v_mfma_f32_16x16x32_bf16 v[112:115], v[144:147], v[180:183], 0
	v_mfma_f32_16x16x32_bf16 v[48:51], v[152:155], v[180:183], 0
	v_mfma_f32_16x16x32_bf16 v[104:107], v[144:147], v[212:215], 0
	v_mfma_f32_16x16x32_bf16 v[40:43], v[152:155], v[212:215], 0
	v_mfma_f32_16x16x32_bf16 v[96:99], v[144:147], v[220:223], 0
	v_mfma_f32_16x16x32_bf16 v[32:35], v[152:155], v[220:223], 0
	v_mfma_f32_16x16x32_bf16 v[120:123], v[148:151], v[176:179], v[120:123]
	v_mfma_f32_16x16x32_bf16 v[56:59], v[156:159], v[176:179], v[56:59]
	v_mfma_f32_16x16x32_bf16 v[112:115], v[148:151], v[184:187], v[112:115]
	v_mfma_f32_16x16x32_bf16 v[48:51], v[156:159], v[184:187], v[48:51]
	v_mfma_f32_16x16x32_bf16 v[104:107], v[148:151], v[216:219], v[104:107]
	v_mfma_f32_16x16x32_bf16 v[40:43], v[156:159], v[216:219], v[40:43]
	v_mfma_f32_16x16x32_bf16 v[96:99], v[148:151], v[224:227], v[96:99]
	v_mfma_f32_16x16x32_bf16 v[32:35], v[156:159], v[224:227], v[32:35]
	s_setprio 0
	s_barrier
	s_add_i32 s54, s54, s13
	s_mov_b32 m0, s54
	ds_read_b128 v[172:175], v189 offset:16384
	ds_read_b128 v[176:179], v189 offset:17408
	ds_read_b128 v[180:183], v189 offset:18432
	ds_read_b128 v[184:187], v189 offset:19456
	ds_read_b128 v[212:215], v189 offset:20480
	ds_read_b128 v[216:219], v189 offset:21504
	ds_read_b128 v[220:223], v189 offset:22528
	ds_read_b128 v[224:227], v189 offset:23552
	global_load_lds_dwordx4 v164, s[8:9]
	s_add_i32 m0, s54, 0x2000
	s_add_u32 s54, s8, 0x40000
	s_addc_u32 s55, s9, 0
	s_add_i32 s53, s53, s13
	global_load_lds_dwordx4 v160, s[8:9]
	s_mov_b32 m0, s53
	s_nop 0
	global_load_lds_dwordx4 v164, s[54:55]
	s_add_i32 m0, s53, 0x2000
	s_nop 0
	global_load_lds_dwordx4 v160, s[54:55]
	s_mov_b32 m0, s10
	s_nop 0
	global_load_lds_dwordx4 v166, vcc
	s_mov_b32 m0, s11
	s_nop 0
	global_load_lds_dwordx4 v162, vcc
	s_waitcnt vmcnt(8)
	s_waitcnt lgkmcnt(0)
	s_barrier
	s_setprio 1
	s_waitcnt lgkmcnt(0)
	v_mfma_f32_16x16x32_bf16 v[92:95], v[128:131], v[172:175], 0
	v_mfma_f32_16x16x32_bf16 v[28:31], v[136:139], v[172:175], 0
	v_mfma_f32_16x16x32_bf16 v[84:87], v[128:131], v[180:183], 0
	v_mfma_f32_16x16x32_bf16 v[20:23], v[136:139], v[180:183], 0
	v_mfma_f32_16x16x32_bf16 v[76:79], v[128:131], v[212:215], 0
	v_mfma_f32_16x16x32_bf16 v[12:15], v[136:139], v[212:215], 0
	v_mfma_f32_16x16x32_bf16 v[72:75], v[128:131], v[220:223], 0
	v_mfma_f32_16x16x32_bf16 v[4:7], v[136:139], v[220:223], 0
	v_mfma_f32_16x16x32_bf16 v[92:95], v[132:135], v[176:179], v[92:95]
	v_mfma_f32_16x16x32_bf16 v[28:31], v[140:143], v[176:179], v[28:31]
	v_mfma_f32_16x16x32_bf16 v[84:87], v[132:135], v[184:187], v[84:87]
	v_mfma_f32_16x16x32_bf16 v[20:23], v[140:143], v[184:187], v[20:23]
	v_mfma_f32_16x16x32_bf16 v[76:79], v[132:135], v[216:219], v[76:79]
	v_mfma_f32_16x16x32_bf16 v[12:15], v[140:143], v[216:219], v[12:15]
	v_mfma_f32_16x16x32_bf16 v[72:75], v[132:135], v[224:227], v[72:75]
	v_mfma_f32_16x16x32_bf16 v[4:7], v[140:143], v[224:227], v[4:7]
	s_setprio 0
	s_setprio 1
	v_mfma_f32_16x16x32_bf16 v[88:91], v[144:147], v[172:175], 0
	v_mfma_f32_16x16x32_bf16 v[24:27], v[152:155], v[172:175], 0
	v_mfma_f32_16x16x32_bf16 v[80:83], v[144:147], v[180:183], 0
	v_mfma_f32_16x16x32_bf16 v[16:19], v[152:155], v[180:183], 0
	v_mfma_f32_16x16x32_bf16 v[68:71], v[144:147], v[212:215], 0
	v_mfma_f32_16x16x32_bf16 v[8:11], v[152:155], v[212:215], 0
	v_mfma_f32_16x16x32_bf16 v[64:67], v[144:147], v[220:223], 0
	v_mfma_f32_16x16x32_bf16 v[0:3], v[152:155], v[220:223], 0
	v_mfma_f32_16x16x32_bf16 v[88:91], v[148:151], v[176:179], v[88:91]
	v_mfma_f32_16x16x32_bf16 v[24:27], v[156:159], v[176:179], v[24:27]
	v_mfma_f32_16x16x32_bf16 v[80:83], v[148:151], v[184:187], v[80:83]
	v_mfma_f32_16x16x32_bf16 v[16:19], v[156:159], v[184:187], v[16:19]
	v_mfma_f32_16x16x32_bf16 v[68:71], v[148:151], v[216:219], v[68:71]
	v_mfma_f32_16x16x32_bf16 v[8:11], v[156:159], v[216:219], v[8:11]
	v_mfma_f32_16x16x32_bf16 v[64:67], v[148:151], v[224:227], v[64:67]
	v_mfma_f32_16x16x32_bf16 v[0:3], v[156:159], v[224:227], v[0:3]
	s_setprio 0
	s_barrier
	s_add_i32 s53, 0, 0x18000
	s_add_i32 s56, 0, 0x1c000
	v_add_u32_e32 v140, s53, v188
	v_add_u32_e32 v156, s56, v188
	ds_read_b128 v[128:131], v140
	ds_read_b128 v[132:135], v140 offset:1024
	ds_read_b128 v[136:139], v140 offset:2048
	ds_read_b128 v[140:143], v140 offset:3072
	ds_read_b128 v[144:147], v156
	ds_read_b128 v[148:151], v156 offset:1024
	ds_read_b128 v[152:155], v156 offset:2048
	ds_read_b128 v[156:159], v156 offset:3072
	s_add_u32 s54, vcc_lo, 0x40000
	s_addc_u32 s55, vcc_hi, 0
	s_mov_b32 m0, s72
	s_nop 0
	ds_read_b128 v[172:175], v189 offset:32768
	ds_read_b128 v[176:179], v189 offset:33792
	ds_read_b128 v[180:183], v189 offset:34816
	ds_read_b128 v[184:187], v189 offset:35840
	ds_read_b128 v[212:215], v189 offset:36864
	ds_read_b128 v[216:219], v189 offset:37888
	ds_read_b128 v[220:223], v189 offset:38912
	ds_read_b128 v[224:227], v189 offset:39936
	global_load_lds_dwordx4 v166, s[54:55]
	s_mov_b32 m0, s73
	s_nop 0
	global_load_lds_dwordx4 v162, s[54:55]
	s_waitcnt vmcnt(8)
	s_waitcnt lgkmcnt(0)
	s_barrier
	s_setprio 1
	s_waitcnt lgkmcnt(0)
	v_mfma_f32_16x16x32_bf16 v[124:127], v[128:131], v[172:175], v[124:127]
	v_mfma_f32_16x16x32_bf16 v[60:63], v[136:139], v[172:175], v[60:63]
	v_mfma_f32_16x16x32_bf16 v[116:119], v[128:131], v[180:183], v[116:119]
	v_mfma_f32_16x16x32_bf16 v[52:55], v[136:139], v[180:183], v[52:55]
	v_mfma_f32_16x16x32_bf16 v[108:111], v[128:131], v[212:215], v[108:111]
	v_mfma_f32_16x16x32_bf16 v[44:47], v[136:139], v[212:215], v[44:47]
	v_mfma_f32_16x16x32_bf16 v[100:103], v[128:131], v[220:223], v[100:103]
	v_mfma_f32_16x16x32_bf16 v[36:39], v[136:139], v[220:223], v[36:39]
	v_mfma_f32_16x16x32_bf16 v[124:127], v[132:135], v[176:179], v[124:127]
	v_mfma_f32_16x16x32_bf16 v[60:63], v[140:143], v[176:179], v[60:63]
	v_mfma_f32_16x16x32_bf16 v[116:119], v[132:135], v[184:187], v[116:119]
	v_mfma_f32_16x16x32_bf16 v[52:55], v[140:143], v[184:187], v[52:55]
	v_mfma_f32_16x16x32_bf16 v[108:111], v[132:135], v[216:219], v[108:111]
	v_mfma_f32_16x16x32_bf16 v[44:47], v[140:143], v[216:219], v[44:47]
	v_mfma_f32_16x16x32_bf16 v[100:103], v[132:135], v[224:227], v[100:103]
	v_mfma_f32_16x16x32_bf16 v[36:39], v[140:143], v[224:227], v[36:39]
	s_setprio 0
	s_setprio 1
	v_mfma_f32_16x16x32_bf16 v[120:123], v[144:147], v[172:175], v[120:123]
	v_mfma_f32_16x16x32_bf16 v[56:59], v[152:155], v[172:175], v[56:59]
	v_mfma_f32_16x16x32_bf16 v[112:115], v[144:147], v[180:183], v[112:115]
	v_mfma_f32_16x16x32_bf16 v[48:51], v[152:155], v[180:183], v[48:51]
	v_mfma_f32_16x16x32_bf16 v[104:107], v[144:147], v[212:215], v[104:107]
	v_mfma_f32_16x16x32_bf16 v[40:43], v[152:155], v[212:215], v[40:43]
	v_mfma_f32_16x16x32_bf16 v[96:99], v[144:147], v[220:223], v[96:99]
	v_mfma_f32_16x16x32_bf16 v[32:35], v[152:155], v[220:223], v[32:35]
	v_mfma_f32_16x16x32_bf16 v[120:123], v[148:151], v[176:179], v[120:123]
	v_mfma_f32_16x16x32_bf16 v[56:59], v[156:159], v[176:179], v[56:59]
	v_mfma_f32_16x16x32_bf16 v[112:115], v[148:151], v[184:187], v[112:115]
	v_mfma_f32_16x16x32_bf16 v[48:51], v[156:159], v[184:187], v[48:51]
	v_mfma_f32_16x16x32_bf16 v[104:107], v[148:151], v[216:219], v[104:107]
	v_mfma_f32_16x16x32_bf16 v[40:43], v[156:159], v[216:219], v[40:43]
	v_mfma_f32_16x16x32_bf16 v[96:99], v[148:151], v[224:227], v[96:99]
	v_mfma_f32_16x16x32_bf16 v[32:35], v[156:159], v[224:227], v[32:35]
	s_setprio 0
	s_barrier
	s_add_i32 s53, s53, s13
	s_add_i32 m0, s53, 0xffffff80
	ds_read_b128 v[172:175], v189 offset:49152
	ds_read_b128 v[176:179], v189 offset:50176
	ds_read_b128 v[180:183], v189 offset:51200
	ds_read_b128 v[184:187], v189 offset:52224
	ds_read_b128 v[212:215], v189 offset:53248
	ds_read_b128 v[216:219], v189 offset:54272
	ds_read_b128 v[220:223], v189 offset:55296
	ds_read_b128 v[224:227], v189 offset:56320
	global_load_lds_dwordx4 v164, s[8:9] offset:128
	s_add_i32 m0, s53, 0x1f80
	s_nop 0
	s_add_i32 s53, s56, s13
	global_load_lds_dwordx4 v160, s[8:9] offset:128
	s_add_u32 s8, s8, 0x40080
	s_addc_u32 s9, s9, 0
	s_mov_b32 m0, s53
	s_nop 0
	global_load_lds_dwordx4 v164, s[8:9]
	s_add_i32 m0, s53, 0x2000
	s_nop 0
	global_load_lds_dwordx4 v160, s[8:9]
	s_add_i32 m0, s12, 0xffffff80
	s_nop 0
	global_load_lds_dwordx4 v166, vcc offset:128
	s_add_i32 m0, s50, 0xffffff80
	s_nop 0
	global_load_lds_dwordx4 v162, vcc offset:128
	s_waitcnt vmcnt(8)
	s_waitcnt lgkmcnt(0)
	s_barrier
	s_setprio 1
	s_waitcnt lgkmcnt(0)
	v_mfma_f32_16x16x32_bf16 v[92:95], v[128:131], v[172:175], v[92:95]
	v_mfma_f32_16x16x32_bf16 v[28:31], v[136:139], v[172:175], v[28:31]
	v_mfma_f32_16x16x32_bf16 v[84:87], v[128:131], v[180:183], v[84:87]
	v_mfma_f32_16x16x32_bf16 v[20:23], v[136:139], v[180:183], v[20:23]
	v_mfma_f32_16x16x32_bf16 v[76:79], v[128:131], v[212:215], v[76:79]
	v_mfma_f32_16x16x32_bf16 v[12:15], v[136:139], v[212:215], v[12:15]
	v_mfma_f32_16x16x32_bf16 v[72:75], v[128:131], v[220:223], v[72:75]
	v_mfma_f32_16x16x32_bf16 v[4:7], v[136:139], v[220:223], v[4:7]
	v_mfma_f32_16x16x32_bf16 v[92:95], v[132:135], v[176:179], v[92:95]
	v_mfma_f32_16x16x32_bf16 v[28:31], v[140:143], v[176:179], v[28:31]
	v_mfma_f32_16x16x32_bf16 v[84:87], v[132:135], v[184:187], v[84:87]
	v_mfma_f32_16x16x32_bf16 v[20:23], v[140:143], v[184:187], v[20:23]
	v_mfma_f32_16x16x32_bf16 v[76:79], v[132:135], v[216:219], v[76:79]
	v_mfma_f32_16x16x32_bf16 v[12:15], v[140:143], v[216:219], v[12:15]
	v_mfma_f32_16x16x32_bf16 v[72:75], v[132:135], v[224:227], v[72:75]
	v_mfma_f32_16x16x32_bf16 v[4:7], v[140:143], v[224:227], v[4:7]
	s_setprio 0
	s_setprio 1
	v_mfma_f32_16x16x32_bf16 v[88:91], v[144:147], v[172:175], v[88:91]
	v_mfma_f32_16x16x32_bf16 v[24:27], v[152:155], v[172:175], v[24:27]
	v_mfma_f32_16x16x32_bf16 v[80:83], v[144:147], v[180:183], v[80:83]
	v_mfma_f32_16x16x32_bf16 v[16:19], v[152:155], v[180:183], v[16:19]
	v_mfma_f32_16x16x32_bf16 v[68:71], v[144:147], v[212:215], v[68:71]
	v_mfma_f32_16x16x32_bf16 v[8:11], v[152:155], v[212:215], v[8:11]
	v_mfma_f32_16x16x32_bf16 v[64:67], v[144:147], v[220:223], v[64:67]
	v_mfma_f32_16x16x32_bf16 v[0:3], v[152:155], v[220:223], v[0:3]
	v_mfma_f32_16x16x32_bf16 v[88:91], v[148:151], v[176:179], v[88:91]
	v_mfma_f32_16x16x32_bf16 v[24:27], v[156:159], v[176:179], v[24:27]
	v_mfma_f32_16x16x32_bf16 v[80:83], v[148:151], v[184:187], v[80:83]
	v_mfma_f32_16x16x32_bf16 v[16:19], v[156:159], v[184:187], v[16:19]
	v_mfma_f32_16x16x32_bf16 v[68:71], v[148:151], v[216:219], v[68:71]
	v_mfma_f32_16x16x32_bf16 v[8:11], v[156:159], v[216:219], v[8:11]
	v_mfma_f32_16x16x32_bf16 v[64:67], v[148:151], v[224:227], v[64:67]
	v_mfma_f32_16x16x32_bf16 v[0:3], v[156:159], v[224:227], v[0:3]
	s_setprio 0
	s_barrier
	s_add_u32 s68, s68, 0x100
	s_addc_u32 s69, s69, 0
	s_add_u32 s4, s4, 0x100
	s_addc_u32 s5, s5, 0
	s_mov_b32 s8, s52
